# flat-release grid barrier: local-last WG does wbl2 + TOP+=1, all WGs poll TOP>=(gen+1)*nx directly (no TOPGEN/XGEN relay)
# speedup vs baseline: 1.0047x; 1.0047x over previous
; __device__ __forceinline__ unsigned xb_ld(unsigned* p)              { return __hip_atomic_load(p, __ATOMIC_RELAXED, __HIP_MEMORY_SCOPE_AGENT); }
; __device__ __forceinline__ unsigned xb_add(unsigned* p, unsigned v) { return __hip_atomic_fetch_add(p, v, __ATOMIC_RELAXED, __HIP_MEMORY_SCOPE_AGENT); }
; #define XB_SPIN(cond, bar) do { unsigned _sp = 0; while (cond) { __builtin_amdgcn_s_sleep(1); \
;     if ((++_sp & 255u) == 0u) { if (xb_ld(&(bar)[XB_TMO])) break; if (_sp > XB_SPIN_CAP) { atomicAdd(&(bar)[XB_TMO], 1u); break; } } } } while (0)
; __device__ __forceinline__ void xcd_barrier(const XcdBarrier& b) {
;     ...
;         const unsigned old = xb_add(&bar[XB_XSUB(b.x)], 1u);
;         const unsigned gen = old / nloc;
;         if (old + 1u == (gen + 1u) * nloc) {
;             __builtin_amdgcn_fence(__ATOMIC_RELEASE, "agent");
;             asm volatile("s_waitcnt vmcnt(0)" ::: "memory");
;             const unsigned og = xb_add(&bar[XB_TOP], 1u);
;             const unsigned tg = og / nx;
;             if (og + 1u == (tg + 1u) * nx) xb_add(&bar[XB_TOPGEN], 1u);
;             else XB_SPIN(xb_ld(&bar[XB_TOPGEN]) == tg, bar);
;             __builtin_amdgcn_fence(__ATOMIC_ACQUIRE, "agent");
;             xb_add(&bar[XB_XGEN(b.x)], 1u);
;             asm volatile("s_waitcnt vmcnt(0)" ::: "memory");
;         } else {
;             XB_SPIN(xb_ld(&bar[XB_XGEN(b.x)]) == gen, bar);
;             __builtin_amdgcn_fence(__ATOMIC_ACQUIRE, "agent");
;             asm volatile("s_waitcnt vmcnt(0)" ::: "memory");
;         }
.LBB0_189:
	s_or_b64 exec, exec, s[10:11]
	v_cvt_f32_u32_e32 v4, v2
	s_waitcnt vmcnt(0)
	v_readfirstlane_b32 s3, v3
	v_sub_u32_e32 v3, 0, v2
	v_rcp_iflag_f32_e32 v4, v4
	v_add_u32_e32 v5, s3, v1
	v_mul_f32_e32 v4, 0x4f7ffffe, v4
	v_cvt_u32_f32_e32 v4, v4
	v_mul_lo_u32 v1, v3, v4
	v_mul_hi_u32 v1, v4, v1
	v_add_u32_e32 v1, v4, v1
	v_mul_hi_u32 v1, v5, v1
	v_mul_lo_u32 v3, v1, v2
	v_sub_u32_e32 v3, v5, v3
	v_add_u32_e32 v4, 1, v1
	v_cmp_ge_u32_e32 vcc, v3, v2
	s_nop 1
	v_cndmask_b32_e32 v1, v1, v4, vcc
	v_sub_u32_e32 v4, v3, v2
	v_cndmask_b32_e32 v3, v3, v4, vcc
	v_add_u32_e32 v4, 1, v1
	v_cmp_ge_u32_e32 vcc, v3, v2
	v_add_u32_e32 v3, 1, v5
	s_nop 0
	v_cndmask_b32_e32 v1, v1, v4, vcc
	v_mul_lo_u32 v4, v2, v1
	v_add_u32_e32 v2, v4, v2
	v_cmp_ne_u32_e32 vcc, v3, v2
	s_cbranch_vccnz .Lxb0_poll
	buffer_wbl2 sc1
	s_waitcnt vmcnt(0) lgkmcnt(0)
	v_mov_b32_e32 v2, 0x303000
	v_mov_b32_e32 v3, 1
	global_atomic_add v2, v3, s[70:71] offset:1024
.Lxb0_poll:
	s_waitcnt lgkmcnt(0)
	v_add_u32_e32 v1, 1, v1
	v_mul_lo_u32 v1, v1, v0
	v_mov_b32_e32 v2, 0x303000
	s_mov_b32 s3, 0
.Lxb0_spin:
	global_load_dword v3, v2, s[70:71] offset:1024 sc1
	s_waitcnt vmcnt(0)
	v_cmp_ge_u32_e32 vcc, v3, v1
	s_cbranch_vccnz .Lxb0_done
	s_add_i32 s3, s3, 1
	s_cmp_lt_u32 s3, 0x40000
	s_cbranch_scc0 .Lxb0_done
	s_sleep 1
	s_branch .Lxb0_spin
.Lxb0_done:
	s_waitcnt vmcnt(0)
	buffer_inv sc1
	s_waitcnt vmcnt(0)
